# GEMM K-loop heads aligned to 64B (s_nop padding)
# baseline (speedup 1.0000x reference)
; template <class Epi, class Sched>
; __device__ __forceinline__ void gemm_phase(LAS unsigned char* lds, const Gemm g, const Sched& S, const Epi& E) {
;     ...
;         const bool has_next = S.next(ui + 1, nxt);
;         const char* nA = has_next ? nxt.A : cA; const char* nB = has_next ? nxt.B : cB;
;         for (int t = 0; t < nt; t += 2) {
;             const bool last = (t == nt - 2);
;             const char* a1 = cA + (size_t)(t + 1) * kstep;
;             const char* a2 = last ? nA : cA + (size_t)(t + 2) * kstep; const char* b2 = last ? nB : cB + (size_t)(t + 2) * kstep;
;     ...
;         for (int a = 0; a < 2; ++a)
; #pragma unroll
;             for (int b = 0; b < 2; ++b)
; #pragma unroll
;                 for (int m = 0; m < 4; ++m)
; #pragma unroll
;                     for (int n = 0; n < 2; ++n) acc[a][b][m][n] = (f32x4){0.f, 0.f, 0.f, 0.f};
;         cur = nxt; cA = nA; cB = nB; ++ui; nt = cur.nt ? cur.nt : g.nt;
.LBB0_250:
	s_cmp_lt_i32 s83, 1
	s_cbranch_scc1 .LBB0_255
	s_and_b64 s[90:91], s[84:85], exec
	s_cselect_b32 s63, s65, s87
	s_cselect_b32 s92, s64, s86
	s_cselect_b32 s93, s79, s89
	s_cselect_b32 s94, s78, s88
	s_add_i32 s95, s83, -2
	s_add_u32 s86, s86, 0x80080
	s_addc_u32 s87, s87, 0
	s_add_u32 s96, s88, 0x100
	v_mov_b32_e32 v0, 0
	s_addc_u32 s97, s89, 0
	s_mov_b32 s88, 0
	v_mov_b32_e32 v1, v0
	v_mov_b32_e32 v2, v0
	v_mov_b32_e32 v3, v0
	v_mov_b32_e32 v4, v0
	v_mov_b32_e32 v5, v0
	v_mov_b32_e32 v6, v0
	v_mov_b32_e32 v7, v0
	v_mov_b32_e32 v16, v0
	v_mov_b32_e32 v17, v0
	v_mov_b32_e32 v18, v0
	v_mov_b32_e32 v19, v0
	v_mov_b32_e32 v20, v0
	v_mov_b32_e32 v21, v0
	v_mov_b32_e32 v22, v0
	v_mov_b32_e32 v23, v0
	v_mov_b32_e32 v32, v0
	v_mov_b32_e32 v33, v0
	v_mov_b32_e32 v34, v0
	v_mov_b32_e32 v35, v0
	v_mov_b32_e32 v36, v0
	v_mov_b32_e32 v37, v0
	v_mov_b32_e32 v38, v0
	v_mov_b32_e32 v39, v0
	v_mov_b32_e32 v48, v0
	v_mov_b32_e32 v49, v0
	v_mov_b32_e32 v50, v0
	v_mov_b32_e32 v51, v0
	v_mov_b32_e32 v52, v0
	v_mov_b32_e32 v53, v0
	v_mov_b32_e32 v54, v0
	v_mov_b32_e32 v55, v0
	v_mov_b32_e32 v8, v0
	v_mov_b32_e32 v9, v0
	v_mov_b32_e32 v10, v0
	v_mov_b32_e32 v11, v0
	v_mov_b32_e32 v12, v0
	v_mov_b32_e32 v13, v0
	v_mov_b32_e32 v14, v0
	v_mov_b32_e32 v15, v0
	v_mov_b32_e32 v24, v0
	v_mov_b32_e32 v25, v0
	v_mov_b32_e32 v26, v0
	v_mov_b32_e32 v27, v0
	v_mov_b32_e32 v28, v0
	v_mov_b32_e32 v29, v0
	v_mov_b32_e32 v30, v0
	v_mov_b32_e32 v31, v0
	v_mov_b32_e32 v40, v0
	v_mov_b32_e32 v41, v0
	v_mov_b32_e32 v42, v0
	v_mov_b32_e32 v43, v0
	v_mov_b32_e32 v44, v0
	v_mov_b32_e32 v45, v0
	v_mov_b32_e32 v46, v0
	v_mov_b32_e32 v47, v0
	v_mov_b32_e32 v56, v0
	v_mov_b32_e32 v57, v0
	v_mov_b32_e32 v58, v0
	v_mov_b32_e32 v59, v0
	v_mov_b32_e32 v60, v0
	v_mov_b32_e32 v61, v0
	v_mov_b32_e32 v62, v0
	v_mov_b32_e32 v63, v0
	v_mov_b32_e32 v64, v0
	v_mov_b32_e32 v65, v0
	v_mov_b32_e32 v66, v0
	v_mov_b32_e32 v67, v0
	v_mov_b32_e32 v68, v0
	v_mov_b32_e32 v69, v0
	v_mov_b32_e32 v70, v0
	v_mov_b32_e32 v71, v0
	v_mov_b32_e32 v80, v0
	v_mov_b32_e32 v81, v0
	v_mov_b32_e32 v82, v0
	v_mov_b32_e32 v83, v0
	v_mov_b32_e32 v84, v0
	v_mov_b32_e32 v85, v0
	v_mov_b32_e32 v86, v0
	v_mov_b32_e32 v87, v0
	v_mov_b32_e32 v96, v0
	v_mov_b32_e32 v97, v0
	v_mov_b32_e32 v98, v0
	v_mov_b32_e32 v99, v0
	v_mov_b32_e32 v100, v0
	v_mov_b32_e32 v101, v0
	v_mov_b32_e32 v102, v0
	v_mov_b32_e32 v103, v0
	v_mov_b32_e32 v112, v0
	v_mov_b32_e32 v113, v0
	v_mov_b32_e32 v114, v0
	v_mov_b32_e32 v115, v0
	v_mov_b32_e32 v116, v0
	v_mov_b32_e32 v117, v0
	v_mov_b32_e32 v118, v0
	v_mov_b32_e32 v119, v0
	v_mov_b32_e32 v72, v0
	v_mov_b32_e32 v73, v0
	v_mov_b32_e32 v74, v0
	v_mov_b32_e32 v75, v0
	v_mov_b32_e32 v76, v0
	v_mov_b32_e32 v77, v0
	v_mov_b32_e32 v78, v0
	v_mov_b32_e32 v79, v0
	v_mov_b32_e32 v88, v0
	v_mov_b32_e32 v89, v0
	v_mov_b32_e32 v90, v0
	v_mov_b32_e32 v91, v0
	v_mov_b32_e32 v92, v0
	v_mov_b32_e32 v93, v0
	v_mov_b32_e32 v94, v0
	v_mov_b32_e32 v95, v0
	v_mov_b32_e32 v104, v0
	v_mov_b32_e32 v105, v0
	v_mov_b32_e32 v106, v0
	v_mov_b32_e32 v107, v0
	v_mov_b32_e32 v108, v0
	v_mov_b32_e32 v109, v0
	v_mov_b32_e32 v110, v0
	v_mov_b32_e32 v111, v0
	v_mov_b32_e32 v120, v0
	v_mov_b32_e32 v121, v0
	v_mov_b32_e32 v122, v0
	v_mov_b32_e32 v123, v0
	v_mov_b32_e32 v124, v0
	v_mov_b32_e32 v125, v0
	v_mov_b32_e32 v126, v0
	v_mov_b32_e32 v127, v0
	.p2alignl 6, 3212836864

; template <class Epi, class Sched>
; __device__ __forceinline__ void gemm_phase(LAS unsigned char* lds, const Gemm g, const Sched& S, const Epi& E) {
;     ...
;         for (int a = 0; a < 2; ++a)
; #pragma unroll
;             for (int b = 0; b < 2; ++b)
; #pragma unroll
;                 for (int m = 0; m < 4; ++m)
; #pragma unroll
;                     for (int n = 0; n < 2; ++n) acc[a][b][m][n] = (f32x4){0.f, 0.f, 0.f, 0.f};
;         cur = nxt; cA = nA; cB = nB; ++ui; nt = cur.nt ? cur.nt : g.nt;
.LBB0_834:
	s_add_u32 s20, s20, 0x80080
	s_addc_u32 s21, s21, 0
	s_add_u32 s11, s22, 0x100
	v_mov_b32_e32 v0, 0
	s_addc_u32 s13, s23, 0
	s_mov_b32 s19, -2
	s_waitcnt lgkmcnt(0)
	v_mov_b32_e32 v1, v0
	v_mov_b32_e32 v2, v0
	v_mov_b32_e32 v3, v0
	v_mov_b32_e32 v4, v0
	v_mov_b32_e32 v5, v0
	v_mov_b32_e32 v6, v0
	v_mov_b32_e32 v7, v0
	v_mov_b32_e32 v16, v0
	v_mov_b32_e32 v17, v0
	v_mov_b32_e32 v18, v0
	v_mov_b32_e32 v19, v0
	v_mov_b32_e32 v20, v0
	v_mov_b32_e32 v21, v0
	v_mov_b32_e32 v22, v0
	v_mov_b32_e32 v23, v0
	v_mov_b32_e32 v32, v0
	v_mov_b32_e32 v33, v0
	v_mov_b32_e32 v34, v0
	v_mov_b32_e32 v35, v0
	v_mov_b32_e32 v36, v0
	v_mov_b32_e32 v37, v0
	v_mov_b32_e32 v38, v0
	v_mov_b32_e32 v39, v0
	v_mov_b32_e32 v48, v0
	v_mov_b32_e32 v49, v0
	v_mov_b32_e32 v50, v0
	v_mov_b32_e32 v51, v0
	v_mov_b32_e32 v52, v0
	v_mov_b32_e32 v53, v0
	v_mov_b32_e32 v54, v0
	v_mov_b32_e32 v55, v0
	v_mov_b32_e32 v8, v0
	v_mov_b32_e32 v9, v0
	v_mov_b32_e32 v10, v0
	v_mov_b32_e32 v11, v0
	v_mov_b32_e32 v12, v0
	v_mov_b32_e32 v13, v0
	v_mov_b32_e32 v14, v0
	v_mov_b32_e32 v15, v0
	v_mov_b32_e32 v24, v0
	v_mov_b32_e32 v25, v0
	v_mov_b32_e32 v26, v0
	v_mov_b32_e32 v27, v0
	v_mov_b32_e32 v28, v0
	v_mov_b32_e32 v29, v0
	v_mov_b32_e32 v30, v0
	v_mov_b32_e32 v31, v0
	v_mov_b32_e32 v40, v0
	v_mov_b32_e32 v41, v0
	v_mov_b32_e32 v42, v0
	v_mov_b32_e32 v43, v0
	v_mov_b32_e32 v44, v0
	v_mov_b32_e32 v45, v0
	v_mov_b32_e32 v46, v0
	v_mov_b32_e32 v47, v0
	v_mov_b32_e32 v56, v0
	v_mov_b32_e32 v57, v0
	v_mov_b32_e32 v58, v0
	v_mov_b32_e32 v59, v0
	v_mov_b32_e32 v60, v0
	v_mov_b32_e32 v61, v0
	v_mov_b32_e32 v62, v0
	v_mov_b32_e32 v63, v0
	v_mov_b32_e32 v64, v0
	v_mov_b32_e32 v65, v0
	v_mov_b32_e32 v66, v0
	v_mov_b32_e32 v67, v0
	v_mov_b32_e32 v68, v0
	v_mov_b32_e32 v69, v0
	v_mov_b32_e32 v70, v0
	v_mov_b32_e32 v71, v0
	v_mov_b32_e32 v80, v0
	v_mov_b32_e32 v81, v0
	v_mov_b32_e32 v82, v0
	v_mov_b32_e32 v83, v0
	v_mov_b32_e32 v84, v0
	v_mov_b32_e32 v85, v0
	v_mov_b32_e32 v86, v0
	v_mov_b32_e32 v87, v0
	v_mov_b32_e32 v96, v0
	v_mov_b32_e32 v97, v0
	v_mov_b32_e32 v98, v0
	v_mov_b32_e32 v99, v0
	v_mov_b32_e32 v100, v0
	v_mov_b32_e32 v101, v0
	v_mov_b32_e32 v102, v0
	v_mov_b32_e32 v103, v0
	v_mov_b32_e32 v112, v0
	v_mov_b32_e32 v113, v0
	v_mov_b32_e32 v114, v0
	v_mov_b32_e32 v115, v0
	v_mov_b32_e32 v116, v0
	v_mov_b32_e32 v117, v0
	v_mov_b32_e32 v118, v0
	v_mov_b32_e32 v119, v0
	v_mov_b32_e32 v72, v0
	v_mov_b32_e32 v73, v0
	v_mov_b32_e32 v74, v0
	v_mov_b32_e32 v75, v0
	v_mov_b32_e32 v76, v0
	v_mov_b32_e32 v77, v0
	v_mov_b32_e32 v78, v0
	v_mov_b32_e32 v79, v0
	v_mov_b32_e32 v88, v0
	v_mov_b32_e32 v89, v0
	v_mov_b32_e32 v90, v0
	v_mov_b32_e32 v91, v0
	v_mov_b32_e32 v92, v0
	v_mov_b32_e32 v93, v0
	v_mov_b32_e32 v94, v0
	v_mov_b32_e32 v95, v0
	v_mov_b32_e32 v104, v0
	v_mov_b32_e32 v105, v0
	v_mov_b32_e32 v106, v0
	v_mov_b32_e32 v107, v0
	v_mov_b32_e32 v108, v0
	v_mov_b32_e32 v109, v0
	v_mov_b32_e32 v110, v0
	v_mov_b32_e32 v111, v0
	v_mov_b32_e32 v120, v0
	v_mov_b32_e32 v121, v0
	v_mov_b32_e32 v122, v0
	v_mov_b32_e32 v123, v0
	v_mov_b32_e32 v124, v0
	v_mov_b32_e32 v125, v0
	v_mov_b32_e32 v126, v0
	v_mov_b32_e32 v127, v0
	.p2alignl 6, 3212836864

; template <class Epi, class Sched>
; __device__ __forceinline__ void gemm_phase(LAS unsigned char* lds, const Gemm g, const Sched& S, const Epi& E) {
;     ...
;         const bool has_next = S.next(ui + 1, nxt);
;         const char* nA = has_next ? nxt.A : cA; const char* nB = has_next ? nxt.B : cB;
;         for (int t = 0; t < nt; t += 2) {
;             const bool last = (t == nt - 2);
;             const char* a1 = cA + (size_t)(t + 1) * kstep;
;             const char* a2 = last ? nA : cA + (size_t)(t + 2) * kstep; const char* b2 = last ? nB : cB + (size_t)(t + 2) * kstep;
;     ...
;         for (int a = 0; a < 2; ++a)
; #pragma unroll
;             for (int b = 0; b < 2; ++b)
; #pragma unroll
;                 for (int m = 0; m < 4; ++m)
; #pragma unroll
;                     for (int n = 0; n < 2; ++n) acc[a][b][m][n] = (f32x4){0.f, 0.f, 0.f, 0.f};
;         cur = nxt; cA = nA; cB = nB; ++ui; nt = cur.nt ? cur.nt : g.nt;
.LBB0_948:
	s_mov_b32 s28, s44
	s_xor_b64 s[44:45], s[56:57], -1
	s_mov_b32 s24, s54
	s_mov_b64 s[30:31], s[58:59]
	s_mov_b64 s[38:39], s[62:63]
	s_and_b64 s[54:55], s[56:57], exec
	s_mov_b32 s91, s29
	s_cselect_b32 s29, s31, s49
	s_cselect_b32 s47, s30, s48
	s_cselect_b32 s56, s39, s53
	s_cselect_b32 s57, s38, s52
	s_add_i32 s58, s1, -2
	s_add_u32 s48, s48, 0x80080
	s_addc_u32 s49, s49, 0
	s_add_u32 s59, s52, 0x100
	v_mov_b32_e32 v0, 0
	s_addc_u32 s60, s53, 0
	s_mov_b32 s52, 0
	v_mov_b32_e32 v1, v0
	v_mov_b32_e32 v2, v0
	v_mov_b32_e32 v3, v0
	v_mov_b32_e32 v4, v0
	v_mov_b32_e32 v5, v0
	v_mov_b32_e32 v6, v0
	v_mov_b32_e32 v7, v0
	v_mov_b32_e32 v16, v0
	v_mov_b32_e32 v17, v0
	v_mov_b32_e32 v18, v0
	v_mov_b32_e32 v19, v0
	v_mov_b32_e32 v20, v0
	v_mov_b32_e32 v21, v0
	v_mov_b32_e32 v22, v0
	v_mov_b32_e32 v23, v0
	v_mov_b32_e32 v32, v0
	v_mov_b32_e32 v33, v0
	v_mov_b32_e32 v34, v0
	v_mov_b32_e32 v35, v0
	v_mov_b32_e32 v36, v0
	v_mov_b32_e32 v37, v0
	v_mov_b32_e32 v38, v0
	v_mov_b32_e32 v39, v0
	v_mov_b32_e32 v48, v0
	v_mov_b32_e32 v49, v0
	v_mov_b32_e32 v50, v0
	v_mov_b32_e32 v51, v0
	v_mov_b32_e32 v52, v0
	v_mov_b32_e32 v53, v0
	v_mov_b32_e32 v54, v0
	v_mov_b32_e32 v55, v0
	v_mov_b32_e32 v8, v0
	v_mov_b32_e32 v9, v0
	v_mov_b32_e32 v10, v0
	v_mov_b32_e32 v11, v0
	v_mov_b32_e32 v12, v0
	v_mov_b32_e32 v13, v0
	v_mov_b32_e32 v14, v0
	v_mov_b32_e32 v15, v0
	v_mov_b32_e32 v24, v0
	v_mov_b32_e32 v25, v0
	v_mov_b32_e32 v26, v0
	v_mov_b32_e32 v27, v0
	v_mov_b32_e32 v28, v0
	v_mov_b32_e32 v29, v0
	v_mov_b32_e32 v30, v0
	v_mov_b32_e32 v31, v0
	v_mov_b32_e32 v40, v0
	v_mov_b32_e32 v41, v0
	v_mov_b32_e32 v42, v0
	v_mov_b32_e32 v43, v0
	v_mov_b32_e32 v44, v0
	v_mov_b32_e32 v45, v0
	v_mov_b32_e32 v46, v0
	v_mov_b32_e32 v47, v0
	v_mov_b32_e32 v56, v0
	v_mov_b32_e32 v57, v0
	v_mov_b32_e32 v58, v0
	v_mov_b32_e32 v59, v0
	v_mov_b32_e32 v60, v0
	v_mov_b32_e32 v61, v0
	v_mov_b32_e32 v62, v0
	v_mov_b32_e32 v63, v0
	v_mov_b32_e32 v64, v0
	v_mov_b32_e32 v65, v0
	v_mov_b32_e32 v66, v0
	v_mov_b32_e32 v67, v0
	v_mov_b32_e32 v68, v0
	v_mov_b32_e32 v69, v0
	v_mov_b32_e32 v70, v0
	v_mov_b32_e32 v71, v0
	v_mov_b32_e32 v80, v0
	v_mov_b32_e32 v81, v0
	v_mov_b32_e32 v82, v0
	v_mov_b32_e32 v83, v0
	v_mov_b32_e32 v84, v0
	v_mov_b32_e32 v85, v0
	v_mov_b32_e32 v86, v0
	v_mov_b32_e32 v87, v0
	v_mov_b32_e32 v96, v0
	v_mov_b32_e32 v97, v0
	v_mov_b32_e32 v98, v0
	v_mov_b32_e32 v99, v0
	v_mov_b32_e32 v100, v0
	v_mov_b32_e32 v101, v0
	v_mov_b32_e32 v102, v0
	v_mov_b32_e32 v103, v0
	v_mov_b32_e32 v108, v0
	v_mov_b32_e32 v109, v0
	v_mov_b32_e32 v110, v0
	v_mov_b32_e32 v111, v0
	v_mov_b32_e32 v116, v0
	v_mov_b32_e32 v117, v0
	v_mov_b32_e32 v118, v0
	v_mov_b32_e32 v119, v0
	v_mov_b32_e32 v72, v0
	v_mov_b32_e32 v73, v0
	v_mov_b32_e32 v74, v0
	v_mov_b32_e32 v75, v0
	v_mov_b32_e32 v76, v0
	v_mov_b32_e32 v77, v0
	v_mov_b32_e32 v78, v0
	v_mov_b32_e32 v79, v0
	v_mov_b32_e32 v88, v0
	v_mov_b32_e32 v89, v0
	v_mov_b32_e32 v90, v0
	v_mov_b32_e32 v91, v0
	v_mov_b32_e32 v92, v0
	v_mov_b32_e32 v93, v0
	v_mov_b32_e32 v94, v0
	v_mov_b32_e32 v95, v0
	v_mov_b32_e32 v104, v0
	v_mov_b32_e32 v105, v0
	v_mov_b32_e32 v106, v0
	v_mov_b32_e32 v107, v0
	v_mov_b32_e32 v112, v0
	v_mov_b32_e32 v113, v0
	v_mov_b32_e32 v114, v0
	v_mov_b32_e32 v115, v0
	v_mov_b32_e32 v120, v0
	v_mov_b32_e32 v121, v0
	v_mov_b32_e32 v122, v0
	v_mov_b32_e32 v123, v0
	v_mov_b32_e32 v124, v0
	v_mov_b32_e32 v125, v0
	v_mov_b32_e32 v126, v0
	v_mov_b32_e32 v127, v0
	.p2alignl 6, 3212836864

; template <class Epi, class Sched>
; __device__ __forceinline__ void gemm_phase(LAS unsigned char* lds, const Gemm g, const Sched& S, const Epi& E) {
;     ...
;         for (int a = 0; a < 2; ++a)
; #pragma unroll
;             for (int b = 0; b < 2; ++b)
; #pragma unroll
;                 for (int m = 0; m < 4; ++m)
; #pragma unroll
;                     for (int n = 0; n < 2; ++n) acc[a][b][m][n] = (f32x4){0.f, 0.f, 0.f, 0.f};
;         cur = nxt; cA = nA; cB = nB; ++ui; nt = cur.nt ? cur.nt : g.nt;
.LBB0_1018:
	s_add_u32 s46, s46, 0x200080
	s_addc_u32 s47, s47, 0
	s_add_u32 s29, s48, 0x100
	v_mov_b32_e32 v0, 0
	s_addc_u32 s31, s49, 0
	s_mov_b32 s64, -2
	v_mov_b32_e32 v1, v0
	v_mov_b32_e32 v2, v0
	v_mov_b32_e32 v3, v0
	v_mov_b32_e32 v4, v0
	v_mov_b32_e32 v5, v0
	v_mov_b32_e32 v6, v0
	v_mov_b32_e32 v7, v0
	v_mov_b32_e32 v12, v0
	v_mov_b32_e32 v13, v0
	v_mov_b32_e32 v14, v0
	v_mov_b32_e32 v15, v0
	v_mov_b32_e32 v20, v0
	v_mov_b32_e32 v21, v0
	v_mov_b32_e32 v22, v0
	v_mov_b32_e32 v23, v0
	v_mov_b32_e32 v28, v0
	v_mov_b32_e32 v29, v0
	v_mov_b32_e32 v30, v0
	v_mov_b32_e32 v31, v0
	v_mov_b32_e32 v36, v0
	v_mov_b32_e32 v37, v0
	v_mov_b32_e32 v38, v0
	v_mov_b32_e32 v39, v0
	v_mov_b32_e32 v44, v0
	v_mov_b32_e32 v45, v0
	v_mov_b32_e32 v46, v0
	v_mov_b32_e32 v47, v0
	v_mov_b32_e32 v52, v0
	v_mov_b32_e32 v53, v0
	v_mov_b32_e32 v54, v0
	v_mov_b32_e32 v55, v0
	v_mov_b32_e32 v8, v0
	v_mov_b32_e32 v9, v0
	v_mov_b32_e32 v10, v0
	v_mov_b32_e32 v11, v0
	v_mov_b32_e32 v16, v0
	v_mov_b32_e32 v17, v0
	v_mov_b32_e32 v18, v0
	v_mov_b32_e32 v19, v0
	v_mov_b32_e32 v24, v0
	v_mov_b32_e32 v25, v0
	v_mov_b32_e32 v26, v0
	v_mov_b32_e32 v27, v0
	v_mov_b32_e32 v32, v0
	v_mov_b32_e32 v33, v0
	v_mov_b32_e32 v34, v0
	v_mov_b32_e32 v35, v0
	v_mov_b32_e32 v40, v0
	v_mov_b32_e32 v41, v0
	v_mov_b32_e32 v42, v0
	v_mov_b32_e32 v43, v0
	v_mov_b32_e32 v48, v0
	v_mov_b32_e32 v49, v0
	v_mov_b32_e32 v50, v0
	v_mov_b32_e32 v51, v0
	v_mov_b32_e32 v56, v0
	v_mov_b32_e32 v57, v0
	v_mov_b32_e32 v58, v0
	v_mov_b32_e32 v59, v0
	v_mov_b32_e32 v60, v0
	v_mov_b32_e32 v61, v0
	v_mov_b32_e32 v62, v0
	v_mov_b32_e32 v63, v0
	v_mov_b32_e32 v64, v0
	v_mov_b32_e32 v65, v0
	v_mov_b32_e32 v66, v0
	v_mov_b32_e32 v67, v0
	v_mov_b32_e32 v68, v0
	v_mov_b32_e32 v69, v0
	v_mov_b32_e32 v70, v0
	v_mov_b32_e32 v71, v0
	v_mov_b32_e32 v76, v0
	v_mov_b32_e32 v77, v0
	v_mov_b32_e32 v78, v0
	v_mov_b32_e32 v79, v0
	v_mov_b32_e32 v84, v0
	v_mov_b32_e32 v85, v0
	v_mov_b32_e32 v86, v0
	v_mov_b32_e32 v87, v0
	v_mov_b32_e32 v92, v0
	v_mov_b32_e32 v93, v0
	v_mov_b32_e32 v94, v0
	v_mov_b32_e32 v95, v0
	v_mov_b32_e32 v100, v0
	v_mov_b32_e32 v101, v0
	v_mov_b32_e32 v102, v0
	v_mov_b32_e32 v103, v0
	v_mov_b32_e32 v108, v0
	v_mov_b32_e32 v109, v0
	v_mov_b32_e32 v110, v0
	v_mov_b32_e32 v111, v0
	v_mov_b32_e32 v112, v0
	v_mov_b32_e32 v113, v0
	v_mov_b32_e32 v114, v0
	v_mov_b32_e32 v115, v0
	v_mov_b32_e32 v72, v0
	v_mov_b32_e32 v73, v0
	v_mov_b32_e32 v74, v0
	v_mov_b32_e32 v75, v0
	v_mov_b32_e32 v80, v0
	v_mov_b32_e32 v81, v0
	v_mov_b32_e32 v82, v0
	v_mov_b32_e32 v83, v0
	v_mov_b32_e32 v88, v0
	v_mov_b32_e32 v89, v0
	v_mov_b32_e32 v90, v0
	v_mov_b32_e32 v91, v0
	v_mov_b32_e32 v96, v0
	v_mov_b32_e32 v97, v0
	v_mov_b32_e32 v98, v0
	v_mov_b32_e32 v99, v0
	v_mov_b32_e32 v104, v0
	v_mov_b32_e32 v105, v0
	v_mov_b32_e32 v106, v0
	v_mov_b32_e32 v107, v0
	v_mov_b32_e32 v116, v0
	v_mov_b32_e32 v117, v0
	v_mov_b32_e32 v118, v0
	v_mov_b32_e32 v119, v0
	v_mov_b32_e32 v120, v0
	v_mov_b32_e32 v121, v0
	v_mov_b32_e32 v122, v0
	v_mov_b32_e32 v123, v0
	v_mov_b32_e32 v124, v0
	v_mov_b32_e32 v125, v0
	v_mov_b32_e32 v126, v0
	v_mov_b32_e32 v127, v0
	.p2alignl 6, 3212836864
